# norm-phase row blocks assigned XCD-locally (wave index permuted so each XCD normalises the rows its own GEMM tiles wrote/read)
# speedup vs baseline: 1.0353x; 1.0050x over previous
.LBB0_101:
	v_writelane_b32 v253, s20, 34
	s_nop 1
	v_writelane_b32 v253, s21, 35
	v_writelane_b32 v253, s18, 36
	s_nop 1
	v_writelane_b32 v253, s19, 37
	v_writelane_b32 v253, s16, 38
	s_nop 1
	v_writelane_b32 v253, s17, 39
	v_writelane_b32 v253, s14, 40
	s_nop 1
	v_writelane_b32 v253, s15, 41
	v_writelane_b32 v253, s12, 42
	s_nop 1
	v_writelane_b32 v253, s13, 43
	v_writelane_b32 v253, s10, 44
	s_nop 1
	v_writelane_b32 v253, s11, 45
	s_or_b64 exec, exec, s[0:1]
	s_lshr_b32 s3, s33, 6
	s_and_b32 s0, s2, 7
	s_lshl_b32 s0, s0, 5
	s_lshr_b32 s1, s2, 3
	s_add_i32 s0, s0, s1
	s_lshl_b32 s0, s0, 3
	s_add_i32 s38, s3, s0
	s_lshl_b32 s40, s50, 3
	s_add_u32 s30, s92, 0x4000000
	v_readlane_b32 s8, v252, 10
	s_addc_u32 s31, s93, 0
	v_readlane_b32 s20, v252, 22
	v_readlane_b32 s21, v252, 23
	s_add_u32 s0, s20, 0x1000
	s_addc_u32 s1, s21, 0
	v_writelane_b32 v253, s0, 46
	s_cmp_lt_i32 s38, 0x8000
	v_readlane_b32 s22, v252, 24
	v_writelane_b32 v253, s1, 47
	s_cselect_b64 s[0:1], -1, 0
	v_writelane_b32 v253, s0, 48
	s_cmpk_lt_i32 s38, 0x2a00
	v_readlane_b32 s23, v252, 25
	v_writelane_b32 v253, s1, 49
	s_cselect_b64 s[0:1], -1, 0
	v_writelane_b32 v253, s0, 50
	v_readlane_b32 s10, v252, 12
	v_readlane_b32 s12, v252, 14
	v_writelane_b32 v253, s1, 51
	s_mul_i32 s0, s3, 0x4400
	s_add_i32 s33, s0, 0
	s_add_u32 s0, s94, 0x2900000
	s_addc_u32 s1, s95, 0
	v_writelane_b32 v253, s0, 52
	v_readlane_b32 s11, v252, 13
	v_readlane_b32 s13, v252, 15
	v_writelane_b32 v253, s1, 53
	s_add_u32 s0, s94, 0x2600000
	s_addc_u32 s1, s95, 0
	v_writelane_b32 v253, s0, 54
	v_readlane_b32 s68, v252, 26
	v_readlane_b32 s69, v252, 27
	v_writelane_b32 v253, s1, 55
	s_add_u32 s0, s94, 0x2400000
	s_addc_u32 s1, s95, 0
	v_writelane_b32 v253, s0, 56
	v_readlane_b32 s14, v252, 16
	v_readlane_b32 s15, v252, 17
	v_writelane_b32 v253, s1, 57
	s_add_u32 s0, s94, 0x2700000
	s_addc_u32 s1, s95, 0
	v_writelane_b32 v253, s0, 58
	s_cmpk_lt_i32 s2, 0xb00
	v_readlane_b32 s72, v252, 30
	v_writelane_b32 v253, s1, 59
	s_cselect_b64 s[0:1], -1, 0
	v_writelane_b32 v253, s0, 60
	s_ashr_i32 s51, s2, 31
	s_ashr_i32 s57, s50, 31
	v_writelane_b32 v253, s1, 61
	s_lshr_b32 s0, s51, 29
	s_add_i32 s0, s2, s0
	s_ashr_i32 s24, s0, 3
	s_and_b32 s0, s0, -8
	s_sub_i32 s25, s2, s0
	s_cmpk_lt_i32 s2, 0x200
	s_cselect_b64 s[0:1], -1, 0
	v_writelane_b32 v253, s0, 62
	s_lshl_b32 s26, s25, 6
	s_add_i32 s22, s38, 1
	v_writelane_b32 v253, s1, 63
	s_lshl_b32 s0, s50, 4
	s_cmpk_lt_i32 s2, 0x100
	v_writelane_b32 v254, s0, 0
	s_cselect_b64 s[0:1], -1, 0
	v_writelane_b32 v254, s0, 1
	s_and_b32 s23, s2, 1
	s_lshl_b32 s27, s25, 5
	v_writelane_b32 v254, s1, 2
	s_ashr_i32 s0, s2, 7
	s_lshl_b32 s1, s0, 1
	s_or_b32 s10, s1, s23
	s_lshl_b32 s0, s0, 6
	s_bfe_u32 s1, s2, 0x60001
	s_or_b32 s12, s0, s1
	s_mov_b32 s0, s10
	s_ashr_i32 s11, s10, 31
	v_writelane_b32 v254, s0, 3
	s_ashr_i32 s13, s12, 31
	v_readlane_b32 s73, v252, 31
	v_writelane_b32 v254, s1, 4
	s_lshl_b64 s[0:1], s[10:11], 19
	v_writelane_b32 v254, s0, 5
	v_readlane_b32 s16, v252, 18
	v_readlane_b32 s17, v252, 19
	v_writelane_b32 v254, s1, 6
	s_mov_b32 s0, s12
	v_writelane_b32 v254, s0, 7
	v_readlane_b32 s18, v252, 20
	v_readlane_b32 s19, v252, 21
	v_writelane_b32 v254, s1, 8
	s_lshl_b64 s[0:1], s[12:13], 19
	v_writelane_b32 v254, s0, 9
	s_cmpk_lt_i32 s2, 0x60
	v_readlane_b32 s9, v252, 11
	v_writelane_b32 v254, s1, 10
	s_cselect_b64 s[0:1], -1, 0
	v_writelane_b32 v254, s0, 11
	s_lshl_b32 s23, s2, 6
	s_ashr_i32 s28, s2, 3
	v_writelane_b32 v254, s1, 12
	s_and_b32 s0, s23, 0x1c0
	v_writelane_b32 v254, s0, 13
	s_lshl_b32 s0, s28, 11
	s_lshl_b32 s1, s28, 12
	s_bitset1_b32 s0, 10
	s_addk_i32 s1, 0xc800
	s_cmp_lt_i32 s28, 8
	s_cselect_b32 s0, s0, s1
	s_ashr_i32 s1, s0, 31
	s_lshl_b64 s[0:1], s[0:1], 11
	v_writelane_b32 v254, s0, 14
	v_readlane_b32 s76, v252, 34
	v_readlane_b32 s77, v252, 35
	v_writelane_b32 v254, s1, 15
	s_lshl_b32 s0, s28, 9
	v_writelane_b32 v254, s0, 16
	s_add_u32 s0, s68, 0x1000
	s_addc_u32 s1, s69, 0
	v_writelane_b32 v254, s0, 17
	s_cmp_lt_i32 s25, 0
	s_mov_b32 s53, 0
	v_writelane_b32 v254, s1, 18
	s_movk_i32 s1, 0x161
	s_cselect_b32 s1, s1, 0x160
	s_mul_i32 s0, s25, 0x41
	s_mul_i32 s1, s25, s1
	s_mul_i32 s25, s25, 33
	s_cselect_b32 s0, s0, s26
	s_cselect_b32 s25, s25, s27
	s_add_i32 s1, s1, s24
	s_mul_hi_i32 s26, s1, 0x2e8ba2e9
	s_lshr_b32 s27, s26, 31
	s_ashr_i32 s26, s26, 5
	s_add_i32 s26, s26, s27
	s_mul_i32 s27, s26, 0xb0
	s_sub_i32 s1, s1, s27
	s_bfe_u32 s27, s1, 0x3001c
	s_add_i32 s27, s1, s27
	s_and_b32 s28, s27, 0xfff8
	s_add_i32 s0, s0, s24
	s_sub_i32 s1, s1, s28
	s_ashr_i32 s28, s0, 31
	s_lshr_b32 s28, s28, 27
	s_add_i32 s28, s0, s28
	s_and_b32 s29, s28, 0xffe0
	s_sub_i32 s0, s0, s29
	s_bfe_i32 s29, s0, 0x80000
	s_bfe_u32 s29, s29, 0x3000c
	s_add_i32 s29, s0, s29
	s_and_b32 s34, s29, 0xf8
	s_sub_i32 s34, s0, s34
	s_add_i32 s0, s25, s24
	s_ashr_i32 s24, s0, 31
	s_lshr_b32 s24, s24, 22
	s_add_i32 s24, s0, s24
	s_and_b32 s25, s24, 0xfffffc00
	s_sub_i32 s35, s0, s25
	s_abs_i32 s25, s40
	v_cvt_f32_u32_e32 v0, s25
	s_sub_i32 s0, 0, s25
	s_sext_i32_i16 s1, s1
	v_readlane_b32 s48, v253, 44
	v_rcp_iflag_f32_e32 v0, v0
	v_readlane_b32 s60, v253, 42
	v_readlane_b32 s62, v253, 40
	v_readlane_b32 s76, v253, 38
	v_mul_f32_e32 v0, 0x4f7ffffe, v0
	v_cvt_u32_f32_e32 v0, v0
	v_readlane_b32 s20, v253, 34
	v_mov_b32_e32 v177, 0
	v_mov_b32_e32 v228, 0x358637bd
	v_readfirstlane_b32 s36, v0
	s_mul_i32 s0, s0, s36
	s_mul_hi_u32 s0, s36, s0
	s_add_i32 s36, s36, s0
	s_lshl_b32 s0, s26, 3
	s_sext_i32_i16 s26, s27
	s_add_i32 s12, s0, s1
	s_ashr_i32 s0, s26, 3
	v_writelane_b32 v254, s0, 19
	s_lshr_b32 s0, s26, 3
	s_bfe_i64 s[0:1], s[0:1], 0x100000
	s_lshl_b64 s[0:1], s[0:1], 19
	v_writelane_b32 v254, s0, 20
	s_sext_i32_i8 s26, s34
	s_mov_b32 s10, s12
	v_writelane_b32 v254, s1, 21
	s_ashr_i32 s0, s28, 5
	s_bfe_i32 s1, s29, 0x80000
	s_lshl_b32 s0, s0, 3
	s_sext_i32_i16 s1, s1
	s_add_i32 s14, s0, s26
	s_lshr_b32 s0, s1, 3
	s_ashr_i32 s7, s1, 3
	s_bfe_i64 s[0:1], s[0:1], 0x100000
	s_lshl_b64 s[0:1], s[0:1], 19
	v_writelane_b32 v254, s0, 22
	s_ashr_i32 s13, s12, 31
	s_ashr_i32 s15, s14, 31
	v_writelane_b32 v254, s1, 23
	s_ashr_i32 s0, s24, 10
	s_lshl_b32 s26, s0, 3
	s_sub_i32 s0, 2, s26
	s_min_u32 s27, s0, 8
	s_lshr_b32 s0, s36, 17
	v_writelane_b32 v254, s10, 24
	s_mul_i32 s1, s0, s25
	s_sub_i32 s1, 0x8000, s1
	v_writelane_b32 v254, s11, 25
	s_lshl_b64 s[10:11], s[12:13], 19
	v_writelane_b32 v254, s10, 26
	s_bfe_i32 s24, s50, 0x1001c
	s_add_i32 s28, s0, 1
	s_sub_i32 s29, s1, s25
	v_writelane_b32 v254, s11, 27
	s_lshl_b64 s[10:11], s[14:15], 19
	s_cmp_ge_u32 s1, s25
	s_cselect_b32 s0, s28, s0
	s_cselect_b32 s1, s29, s1
	s_add_i32 s28, s0, 1
	s_sub_i32 s29, s1, s25
	s_cmp_ge_u32 s1, s25
	s_cselect_b32 s0, s28, s0
	v_writelane_b32 v254, s10, 28
	s_cselect_b32 s1, s29, s1
	s_xor_b32 s0, s0, s24
	v_writelane_b32 v254, s11, 29
	s_sub_i32 s10, s0, s24
	s_and_b32 s28, s10, 3
	s_or_b32 s29, s1, s28
	s_cmp_eq_u32 s29, 0
	s_cselect_b64 s[0:1], -1, 0
	s_cmp_lg_u32 s29, 0
	s_cselect_b64 s[12:13], -1, 0
	s_abs_i32 s29, s10
	v_cvt_f32_u32_e32 v0, s29
	s_sub_i32 s34, 0, s29
	v_writelane_b32 v254, s12, 30
	s_mul_i32 s72, s10, s38
	v_rcp_iflag_f32_e32 v0, v0
	v_writelane_b32 v254, s13, 31
	v_cndmask_b32_e64 v227, 0, 1, s[0:1]
	v_mov_b32_e32 v229, 0x260
	v_mul_f32_e32 v0, 0x4f7ffffe, v0
	v_cvt_u32_f32_e32 v0, v0
	v_mov_b32_e32 v230, 1
	v_mov_b64_e32 v[178:179], 0xb00
	v_mov_b64_e32 v[180:181], 0xaff
	v_readfirstlane_b32 s37, v0
	s_mul_i32 s34, s34, s37
	s_mul_hi_u32 s34, s37, s34
	s_add_i32 s37, s37, s34
	s_lshr_b32 s34, s37, 21
	s_mul_i32 s34, s34, s29
	s_sub_i32 s34, 0x800, s34
	s_sub_i32 s37, s34, s29
	s_cmp_ge_u32 s34, s29
	s_cselect_b32 s34, s37, s34
	s_sub_i32 s37, s34, s29
	s_cmp_ge_u32 s34, s29
	s_cselect_b32 s29, s37, s34
	s_cmp_lg_u32 s29, 0
	s_cselect_b64 s[12:13], -1, 0
	v_writelane_b32 v254, s12, 32
	s_cmpk_gt_i32 s72, 0x3fff
	v_mov_b64_e32 v[182:183], 0x200
	v_writelane_b32 v254, s13, 33
	s_cselect_b64 s[12:13], -1, 0
	s_add_i32 s29, s72, 0xffffc000
	s_lshr_b32 s29, s29, 12
	s_ashr_i32 s73, s72, 31
	v_writelane_b32 v254, s12, 34
	s_add_i32 s11, s29, 8
	s_lshr_b32 s29, s73, 21
	v_writelane_b32 v254, s13, 35
	s_add_i32 s29, s72, s29
	v_writelane_b32 v254, s11, 36
	s_ashr_i32 s11, s29, 11
	s_cmp_gt_i32 s10, 0
	s_cselect_b64 s[12:13], -1, 0
	s_lshr_b32 s29, s36, 18
	s_mul_i32 s34, s29, s25
	s_sub_i32 s34, 0x4000, s34
	s_add_i32 s36, s29, 1
	s_sub_i32 s37, s34, s25
	s_cmp_ge_u32 s34, s25
	s_cselect_b32 s29, s36, s29
	s_cselect_b32 s34, s37, s34
	s_add_i32 s36, s29, 1
	s_cmp_ge_u32 s34, s25
	s_cselect_b32 s25, s36, s29
	s_xor_b32 s25, s25, s24
	v_writelane_b32 v254, s11, 37
	s_sub_i32 s11, s25, s24
	v_cvt_f32_i32_e32 v0, s11
	s_mul_i32 s24, s11, s40
	s_and_b32 s25, s11, 1
	s_sub_i32 s24, s25, s24
	v_rcp_iflag_f32_e32 v1, v0
	v_writelane_b32 v254, s12, 38
	s_cmpk_eq_i32 s24, 0xc000
	s_mov_b32 s24, 0x44800000
	v_mul_f32_e32 v1, 0x44800000, v1
	v_trunc_f32_e32 v1, v1
	v_writelane_b32 v254, s13, 39
	v_fma_f32 v2, -v1, v0, s24
	s_cselect_b64 s[12:13], -1, 0
	s_ashr_i32 s24, s11, 30
	s_or_b32 s29, s24, 1
	v_cmp_ge_f32_e64 s[24:25], |v2|, |v0|
	v_cvt_i32_f32_e32 v0, v1
	s_and_b64 s[24:25], s[24:25], exec
	v_cvt_f32_ubyte0_e32 v1, s27
	v_rcp_iflag_f32_e32 v2, v1
	v_readfirstlane_b32 s25, v0
	v_cvt_f32_i32_e32 v0, s35
	s_cselect_b32 s24, s29, 0
	s_add_i32 s24, s25, s24
	s_mul_i32 s24, s24, s11
	s_and_b32 s24, s24, 0xffff
	v_mul_f32_e32 v2, v0, v2
	v_writelane_b32 v254, s12, 40
	s_cmpk_eq_i32 s24, 0x400
	v_trunc_f32_e32 v2, v2
	v_writelane_b32 v254, s13, 41
	s_cselect_b64 s[12:13], -1, 0
	s_ashr_i32 s24, s35, 30
	v_fma_f32 v0, -v2, v1, v0
	s_or_b32 s29, s24, 1
	v_cmp_ge_f32_e64 s[24:25], |v0|, v1
	v_cvt_i32_f32_e32 v0, v2
	s_and_b64 s[24:25], s[24:25], exec
	s_cselect_b32 s24, s29, 0
	v_writelane_b32 v254, s12, 42
	v_readfirstlane_b32 s25, v0
	s_add_i32 s24, s25, s24
	s_mul_i32 s25, s24, s27
	s_sub_i32 s25, s35, s25
	s_mul_i32 s27, s10, s40
	s_sext_i32_i16 s25, s25
	s_sub_i32 s28, s28, s27
	s_add_i32 s16, s26, s25
	s_bfe_i64 s[26:27], s[24:25], 0x100000
	v_writelane_b32 v254, s13, 43
	s_lshl_b64 s[12:13], s[26:27], 19
	v_writelane_b32 v254, s12, 44
	s_ashr_i32 s17, s16, 31
	s_add_i32 s28, s28, 0x8000
	v_writelane_b32 v254, s13, 45
	s_mov_b32 s12, s16
	v_writelane_b32 v254, s12, 46
	s_sext_i32_i16 s0, s24
	v_writelane_b32 v255, s0, 0
	v_writelane_b32 v254, s13, 47
	s_lshl_b64 s[12:13], s[16:17], 19
	v_writelane_b32 v254, s12, 48
	s_cmp_eq_u32 s28, 0
	v_mov_b64_e32 v[184:185], 0x1ff
	v_writelane_b32 v254, s13, 49
	s_cselect_b64 s[12:13], -1, 0
	v_writelane_b32 v254, s12, 50
	s_cmp_lg_u32 s28, 0
	v_mov_b64_e32 v[188:189], 0xff
	v_writelane_b32 v254, s13, 51
	s_cselect_b64 s[12:13], -1, 0
	v_writelane_b32 v254, s12, 52
	s_ashr_i32 s39, s38, 31
	v_bfrev_b32_e32 v231, 0.5
	v_writelane_b32 v254, s13, 53
	s_lshl_b64 s[12:13], s[38:39], 11
	s_add_u32 s16, s92, s12
	v_writelane_b32 v254, s12, 54
	s_addc_u32 s17, s93, s13
	s_ashr_i32 s41, s40, 31
	v_writelane_b32 v254, s13, 55
	v_writelane_b32 v254, s16, 56
	s_lshl_b64 s[12:13], s[40:41], 11
	v_writelane_b32 v255, s40, 1
	v_writelane_b32 v254, s17, 57
	s_lshl_b64 s[16:17], s[72:73], 11
	s_add_u32 s18, s92, s16
	s_addc_u32 s19, s93, s17
	v_writelane_b32 v254, s18, 58
	v_writelane_b32 v255, s41, 2
	v_mov_b32_e32 v232, 0x100
	v_writelane_b32 v254, s19, 59
	v_writelane_b32 v254, s38, 60
	s_lshl_b64 s[26:27], s[38:39], 12
	s_add_u32 s8, s8, s26
	s_addc_u32 s9, s9, s27
	s_lshl_b64 s[0:1], s[40:41], 12
	v_writelane_b32 v255, s0, 3
	v_writelane_b32 v254, s39, 61
	v_writelane_b32 v254, s8, 62
	v_writelane_b32 v255, s1, 4
	s_add_u32 s0, s16, 0x4b00000
	v_writelane_b32 v255, s0, 5
	v_writelane_b32 v255, s16, 6
	s_addc_u32 s0, s17, 0
	v_readlane_b32 s18, v253, 36
	v_writelane_b32 v255, s17, 7
	v_writelane_b32 v255, s0, 8
	s_lshl_b32 s0, s3, 3
	s_add_i32 s0, s23, s0
	v_writelane_b32 v255, s0, 9
	v_writelane_b32 v255, s11, 10
	s_mul_i32 s0, s11, s22
	v_writelane_b32 v255, s0, 11
	s_mul_hi_i32 s0, s14, 0x160000
	v_writelane_b32 v255, s0, 12
	s_mov_b32 s0, s14
	v_writelane_b32 v255, s0, 13
	v_writelane_b32 v254, s9, 63
	s_mov_b32 s89, 0xf800000
	v_writelane_b32 v255, s1, 14
	s_mul_i32 s0, s14, 0x160000
	v_writelane_b32 v255, s0, 15
	s_mul_hi_i32 s0, s7, 0x160000
	v_writelane_b32 v255, s0, 16
	v_writelane_b32 v255, s7, 17
	s_mul_i32 s0, s7, 0x160000
	v_writelane_b32 v255, s0, 18
	s_lshl_b32 s0, s50, 6
	v_writelane_b32 v255, s0, 19
	s_add_i32 s0, 0, 0x23fe0
	v_writelane_b32 v255, s0, 20
	s_add_i32 s0, 0, 0x23fe4
	v_writelane_b32 v255, s0, 21
	s_add_i32 s0, 0, 0x23ff0
	v_writelane_b32 v255, s0, 22
	s_add_i32 s0, 0, 0x12100
	v_writelane_b32 v255, s0, 23
	v_writelane_b32 v255, s6, 24
	v_writelane_b32 v255, s10, 25
	v_writelane_b32 v255, s72, 26
	s_movk_i32 s28, 0x5800
	s_movk_i32 s29, 0x1600
	v_writelane_b32 v255, s73, 27
	v_writelane_b32 v255, s12, 28
	s_mov_b64 s[0:1], -1
	s_mov_b64 s[24:25], 0x80
	s_mov_b64 s[26:27], 0x100
	s_mov_b64 s[84:85], 0x20000
	s_mov_b32 s88, 0x3b3504f3
	s_mov_b32 s56, 0x3b000000
	s_mov_b32 s14, s53
	v_readlane_b32 s49, v253, 45
	v_readlane_b32 s61, v253, 43
	v_readlane_b32 s63, v253, 41
	v_readlane_b32 s77, v253, 39
	v_readlane_b32 s19, v253, 37
	v_readlane_b32 s21, v253, 35
	v_writelane_b32 v255, s13, 29
	v_readlane_b32 s70, v252, 28
	v_readlane_b32 s71, v252, 29
	v_readlane_b32 s74, v252, 32
	v_readlane_b32 s75, v252, 33
	v_readlane_b32 s78, v252, 36
	v_readlane_b32 s79, v252, 37
	v_readlane_b32 s80, v252, 38
	v_readlane_b32 s81, v252, 39
	v_readlane_b32 s82, v252, 40
	v_readlane_b32 s83, v252, 41
	s_waitcnt lgkmcnt(0)
	s_barrier
	s_branch .LBB0_105
